# v20 + back-edge rotation (7.11): in the three rotated K=1024 loops the taken s_cbranch now precedes barrier a4 so the MMA p4 block starts with its first MFMA right after the barrier release
# speedup vs baseline: 1.0100x; 1.0100x over previous
; #define PG8_STAGE(bufoff, gbase, voff) do { _Pragma("unroll") for (int _i = 0; _i < 2; ++_i) \
;         __builtin_amdgcn_global_load_lds((const unsigned*)((const char*)(gbase) + (voff)[_i]), (LAS unsigned*)(lds + (bufoff) + ldsw + _i * 8192), 16, 0, 0); } while (0)
; #define PG8_LDA(dst, b, h) do { _Pragma("unroll") for (int m = 0; m < 4; ++m) _Pragma("unroll") for (int k = 0; k < 2; ++k) dst[m][k] = *(const LAS bf16x8*)(lds + PG8_SA(b, h) + aoff + m * 2048 + k * 1024); } while (0)
; #define PG8_LDB(dst, b, h) do { _Pragma("unroll") for (int n = 0; n < 2; ++n) _Pragma("unroll") for (int k = 0; k < 2; ++k) dst[n][k] = *(const LAS bf16x8*)(lds + PG8_SB(b, h) + boff + n * 2048 + k * 1024); } while (0)
; #define PG8_MMA(ai, bj, At, Bt) do { __builtin_amdgcn_s_setprio(1); _Pragma("unroll") for (int m = 0; m < 4; ++m) _Pragma("unroll") for (int n = 0; n < 2; ++n) _Pragma("unroll") for (int k = 0; k < 2; ++k) \
;         acc[ai][bj][m][n] = __builtin_amdgcn_mfma_f32_16x16x32_bf16(Bt[n][k], At[m][k], acc[ai][bj][m][n], 0, 0, 0); __builtin_amdgcn_s_setprio(0); } while (0)
; #define PG8_WAIT_V(n) asm volatile("s_waitcnt vmcnt(" #n ")" ::: "memory")
; #define PG8_WAIT_L(n) asm volatile("s_waitcnt lgkmcnt(" #n ")" ::: "memory")
; #define PG8_BAR __builtin_amdgcn_s_barrier()
; #define PG8_SCHED __builtin_amdgcn_sched_barrier(0)
; template <class Epi, class Sched>
; __device__ __forceinline__ void gemm_phase(LAS unsigned char* lds, const int lda, const int ldb, const int K, const Sched& S, const Epi& E) {
;     ...
;         for (int t = 0; t < nt; t += 2) {
;             const bool last = (t == nt - 2);
;             const char* a1 = cA + (size_t)(t + 1) * kstep;
;             const char* a2 = last ? nA : cA + (size_t)(t + 2) * kstep; const char* b2 = last ? nB : cB + (size_t)(t + 2) * kstep;
;             const char* a3 = a2 + kstep; const char* b3 = b2 + kstep;
;             PG8_LDB(B0, 0, 0); PG8_LDB(B1, 0, 1); PG8_SCHED; PG8_LDA(At, 0, 0); PG8_STAGE(PG8_SA(1, 1), a1 + hstepA, voffA);
;             PG8_WAIT_V(8); PG8_WAIT_L(0); PG8_BAR; PG8_MMA(0, 0, At, B0); PG8_MMA(0, 1, At, B1); PG8_BAR; PG8_SCHED;
;             PG8_LDA(At, 0, 1); PG8_STAGE(PG8_SB(0, 0), b2, voffB); PG8_STAGE(PG8_SB(0, 1), b2 + hstepB, voffB); PG8_STAGE(PG8_SA(0, 0), a2, voffA);
;             PG8_WAIT_V(8); PG8_WAIT_L(0); PG8_BAR; PG8_MMA(1, 0, At, B0); PG8_MMA(1, 1, At, B1); PG8_BAR; PG8_SCHED;
.LBB0_240:
	s_lshl_b32 s20, s20, 8
	s_ashr_i32 s21, s20, 31
	s_add_u32 s22, s22, 0x40080
	s_addc_u32 s23, s23, 0
	s_add_u32 s13, s24, 0x100
	s_addc_u32 s15, s25, 0
	s_mov_b32 s65, -2
	v_lshl_add_u64 v[214:215], s[20:21], 2, v[204:205]
	v_add_u32_e32 v230, 0x80, v200
	v_add_u32_e32 v231, 0x80, v196
	v_add_u32_e32 v232, 0x80, v202
	v_add_u32_e32 v233, 0x80, v198
	s_add_u32 s21, s22, 0xfffc0080
	s_addc_u32 s24, s23, -1
	s_cmp_eq_u32 s65, 12
	s_cselect_b32 s29, s17, s24
	s_cselect_b32 s28, s16, s21
	s_cselect_b32 s31, s19, s15
	s_cselect_b32 s30, s18, s13
	s_add_i32 s72, s50, s3
	s_add_i32 m0, s37, 0xc000
	s_add_i32 s71, s37, 0xe000
	s_add_i32 s73, s72, 0x2000
	s_add_u32 s48, s30, 0x40000
	s_addc_u32 s49, s31, 0
	s_add_i32 s74, s51, s3
	s_add_i32 s75, s74, 0x2000
	s_add_i32 s76, 0, 0x18000
	s_add_i32 s77, 0, 0x1c000
	s_add_u32 s26, s28, 0x40000
	s_addc_u32 s27, s29, 0
	s_add_i32 s68, s76, s3
	s_add_i32 s21, s68, 0x2000
	s_add_u32 s24, s30, 0x40080
	s_addc_u32 s25, s31, 0
	s_add_i32 s70, s77, s3
	s_add_i32 s69, s70, 0x2000
	s_cmp_lg_u32 s65, 12
	global_load_lds_dwordx4 v206, s[22:23]
	s_mov_b32 m0, s71
	s_nop 0
	global_load_lds_dwordx4 v208, s[22:23]
	s_waitcnt vmcnt(8)
	s_waitcnt lgkmcnt(0)
	s_barrier
	v_mfma_f32_16x16x32_bf16 v[126:129], v[130:133], v[162:165], 0
	v_mfma_f32_16x16x32_bf16 v[118:121], v[138:141], v[162:165], 0
	v_mfma_f32_16x16x32_bf16 v[110:113], v[130:133], v[170:173], 0
	v_mfma_f32_16x16x32_bf16 v[102:105], v[138:141], v[170:173], 0
	v_mfma_f32_16x16x32_bf16 v[94:97], v[130:133], v[178:181], 0
	v_mfma_f32_16x16x32_bf16 v[86:89], v[138:141], v[178:181], 0
	v_mfma_f32_16x16x32_bf16 v[78:81], v[130:133], v[186:189], 0
	v_mfma_f32_16x16x32_bf16 v[70:73], v[138:141], v[186:189], 0
	v_mfma_f32_16x16x32_bf16 v[126:129], v[134:137], v[166:169], v[126:129]
	v_mfma_f32_16x16x32_bf16 v[118:121], v[142:145], v[166:169], v[118:121]
	v_mfma_f32_16x16x32_bf16 v[110:113], v[134:137], v[174:177], v[110:113]
	v_mfma_f32_16x16x32_bf16 v[102:105], v[142:145], v[174:177], v[102:105]
	v_mfma_f32_16x16x32_bf16 v[94:97], v[134:137], v[182:185], v[94:97]
	v_mfma_f32_16x16x32_bf16 v[86:89], v[142:145], v[182:185], v[86:89]
	v_mfma_f32_16x16x32_bf16 v[78:81], v[134:137], v[190:193], v[78:81]
	v_mfma_f32_16x16x32_bf16 v[70:73], v[142:145], v[190:193], v[70:73]
	v_mfma_f32_16x16x32_bf16 v[122:125], v[146:149], v[162:165], 0
	v_mfma_f32_16x16x32_bf16 v[114:117], v[154:157], v[162:165], 0
	v_mfma_f32_16x16x32_bf16 v[106:109], v[146:149], v[170:173], 0
	v_mfma_f32_16x16x32_bf16 v[98:101], v[154:157], v[170:173], 0
	v_mfma_f32_16x16x32_bf16 v[90:93], v[146:149], v[178:181], 0
	v_mfma_f32_16x16x32_bf16 v[82:85], v[154:157], v[178:181], 0
	v_mfma_f32_16x16x32_bf16 v[74:77], v[146:149], v[186:189], 0
	v_mfma_f32_16x16x32_bf16 v[66:69], v[154:157], v[186:189], 0
	v_mfma_f32_16x16x32_bf16 v[122:125], v[150:153], v[166:169], v[122:125]
	v_mfma_f32_16x16x32_bf16 v[114:117], v[158:161], v[166:169], v[114:117]
	v_mfma_f32_16x16x32_bf16 v[106:109], v[150:153], v[174:177], v[106:109]
	v_mfma_f32_16x16x32_bf16 v[98:101], v[158:161], v[174:177], v[98:101]
	v_mfma_f32_16x16x32_bf16 v[90:93], v[150:153], v[182:185], v[90:93]
	v_mfma_f32_16x16x32_bf16 v[82:85], v[158:161], v[182:185], v[82:85]
	v_mfma_f32_16x16x32_bf16 v[74:77], v[150:153], v[190:193], v[74:77]
	v_mfma_f32_16x16x32_bf16 v[66:69], v[158:161], v[190:193], v[66:69]
	s_barrier
	s_mov_b32 m0, s72
	ds_read_b128 v[162:165], v219 offset:16384
	ds_read_b128 v[166:169], v219 offset:17408
	ds_read_b128 v[170:173], v219 offset:18432
	ds_read_b128 v[174:177], v219 offset:19456
	ds_read_b128 v[178:181], v219 offset:20480
	ds_read_b128 v[182:185], v219 offset:21504
	ds_read_b128 v[186:189], v219 offset:22528
	ds_read_b128 v[190:193], v219 offset:23552
	global_load_lds_dwordx4 v200, s[30:31]
	s_mov_b32 m0, s73
	s_nop 0
	global_load_lds_dwordx4 v196, s[30:31]
	s_mov_b32 m0, s74
	s_nop 0
	global_load_lds_dwordx4 v200, s[48:49]
	s_mov_b32 m0, s75
	s_nop 0
	global_load_lds_dwordx4 v196, s[48:49]
	s_mov_b32 m0, s37
	s_nop 0
	global_load_lds_dwordx4 v202, s[28:29]
	s_mov_b32 m0, s38
	s_nop 0
	global_load_lds_dwordx4 v198, s[28:29]
	s_waitcnt vmcnt(8)
	s_waitcnt lgkmcnt(0)
	s_barrier
	v_mfma_f32_16x16x32_bf16 v[62:65], v[130:133], v[162:165], 0
	v_mfma_f32_16x16x32_bf16 v[54:57], v[138:141], v[162:165], 0
	v_mfma_f32_16x16x32_bf16 v[46:49], v[130:133], v[170:173], 0
	v_mfma_f32_16x16x32_bf16 v[38:41], v[138:141], v[170:173], 0
	v_mfma_f32_16x16x32_bf16 v[30:33], v[130:133], v[178:181], 0
	v_mfma_f32_16x16x32_bf16 v[22:25], v[138:141], v[178:181], 0
	v_mfma_f32_16x16x32_bf16 v[14:17], v[130:133], v[186:189], 0
	v_mfma_f32_16x16x32_bf16 v[6:9], v[138:141], v[186:189], 0
	v_mfma_f32_16x16x32_bf16 v[62:65], v[134:137], v[166:169], v[62:65]
	v_mfma_f32_16x16x32_bf16 v[54:57], v[142:145], v[166:169], v[54:57]
	v_mfma_f32_16x16x32_bf16 v[46:49], v[134:137], v[174:177], v[46:49]
	v_mfma_f32_16x16x32_bf16 v[38:41], v[142:145], v[174:177], v[38:41]
	v_mfma_f32_16x16x32_bf16 v[30:33], v[134:137], v[182:185], v[30:33]
	v_mfma_f32_16x16x32_bf16 v[22:25], v[142:145], v[182:185], v[22:25]
	v_mfma_f32_16x16x32_bf16 v[14:17], v[134:137], v[190:193], v[14:17]
	v_mfma_f32_16x16x32_bf16 v[6:9], v[142:145], v[190:193], v[6:9]
	v_mfma_f32_16x16x32_bf16 v[58:61], v[146:149], v[162:165], 0
	v_mfma_f32_16x16x32_bf16 v[50:53], v[154:157], v[162:165], 0
	v_mfma_f32_16x16x32_bf16 v[42:45], v[146:149], v[170:173], 0
	v_mfma_f32_16x16x32_bf16 v[34:37], v[154:157], v[170:173], 0
	v_mfma_f32_16x16x32_bf16 v[26:29], v[146:149], v[178:181], 0
	v_mfma_f32_16x16x32_bf16 v[18:21], v[154:157], v[178:181], 0
	v_mfma_f32_16x16x32_bf16 v[10:13], v[146:149], v[186:189], 0
	v_mfma_f32_16x16x32_bf16 v[2:5], v[154:157], v[186:189], 0
	v_mfma_f32_16x16x32_bf16 v[58:61], v[150:153], v[166:169], v[58:61]
	v_mfma_f32_16x16x32_bf16 v[50:53], v[158:161], v[166:169], v[50:53]
	v_mfma_f32_16x16x32_bf16 v[42:45], v[150:153], v[174:177], v[42:45]
	v_mfma_f32_16x16x32_bf16 v[34:37], v[158:161], v[174:177], v[34:37]
	v_mfma_f32_16x16x32_bf16 v[26:29], v[150:153], v[182:185], v[26:29]
	v_mfma_f32_16x16x32_bf16 v[18:21], v[158:161], v[182:185], v[18:21]
	v_mfma_f32_16x16x32_bf16 v[10:13], v[150:153], v[190:193], v[10:13]
	v_mfma_f32_16x16x32_bf16 v[2:5], v[158:161], v[190:193], v[2:5]
	s_barrier
	s_branch .Lpeel1_join
; #define PG8_MMA(ai, bj, At, Bt) do { __builtin_amdgcn_s_setprio(1); _Pragma("unroll") for (int m = 0; m < 4; ++m) _Pragma("unroll") for (int n = 0; n < 2; ++n) _Pragma("unroll") for (int k = 0; k < 2; ++k) \
;         acc[ai][bj][m][n] = __builtin_amdgcn_mfma_f32_16x16x32_bf16(Bt[n][k], At[m][k], acc[ai][bj][m][n], 0, 0, 0); __builtin_amdgcn_s_setprio(0); } while (0)
; #define PG8_WAIT_V(n) asm volatile("s_waitcnt vmcnt(" #n ")" ::: "memory")
; #define PG8_WAIT_L(n) asm volatile("s_waitcnt lgkmcnt(" #n ")" ::: "memory")
; #define PG8_BAR __builtin_amdgcn_s_barrier()
; #define PG8_SCHED __builtin_amdgcn_sched_barrier(0)
; template <class Epi, class Sched>
; __device__ __forceinline__ void gemm_phase(LAS unsigned char* lds, const int lda, const int ldb, const int K, const Sched& S, const Epi& E) {
;     ...
;             PG8_WAIT_V(8); PG8_WAIT_L(0); PG8_BAR;
;             if (last) E.pre(cur, wr, fr, rsv);
;             PG8_MMA(1, 0, At, B0); PG8_MMA(1, 1, At, B1); PG8_BAR; PG8_SCHED;
;         }
.Lrot1:
	s_barrier
.LBB0_241:
	v_mfma_f32_16x16x32_bf16 v[62:65], v[146:149], v[186:189], v[62:65]
	v_mfma_f32_16x16x32_bf16 v[54:57], v[154:157], v[186:189], v[54:57]
	v_mfma_f32_16x16x32_bf16 v[46:49], v[146:149], v[178:181], v[46:49]
	v_mfma_f32_16x16x32_bf16 v[38:41], v[154:157], v[178:181], v[38:41]
	v_mfma_f32_16x16x32_bf16 v[30:33], v[146:149], v[170:173], v[30:33]
	v_mfma_f32_16x16x32_bf16 v[22:25], v[154:157], v[170:173], v[22:25]
	v_mfma_f32_16x16x32_bf16 v[14:17], v[146:149], v[162:165], v[14:17]
	v_mfma_f32_16x16x32_bf16 v[6:9], v[154:157], v[162:165], v[6:9]
	v_mfma_f32_16x16x32_bf16 v[62:65], v[150:153], v[190:193], v[62:65]
	v_mfma_f32_16x16x32_bf16 v[54:57], v[158:161], v[190:193], v[54:57]
	v_mfma_f32_16x16x32_bf16 v[46:49], v[150:153], v[182:185], v[46:49]
	v_mfma_f32_16x16x32_bf16 v[38:41], v[158:161], v[182:185], v[38:41]
	v_mfma_f32_16x16x32_bf16 v[30:33], v[150:153], v[174:177], v[30:33]
	v_mfma_f32_16x16x32_bf16 v[22:25], v[158:161], v[174:177], v[22:25]
	v_mfma_f32_16x16x32_bf16 v[14:17], v[150:153], v[166:169], v[14:17]
	v_mfma_f32_16x16x32_bf16 v[6:9], v[158:161], v[166:169], v[6:9]
	v_mfma_f32_16x16x32_bf16 v[58:61], v[130:133], v[186:189], v[58:61]
	v_mfma_f32_16x16x32_bf16 v[50:53], v[138:141], v[186:189], v[50:53]
	v_mfma_f32_16x16x32_bf16 v[42:45], v[130:133], v[178:181], v[42:45]
	v_mfma_f32_16x16x32_bf16 v[34:37], v[138:141], v[178:181], v[34:37]
	v_mfma_f32_16x16x32_bf16 v[26:29], v[130:133], v[170:173], v[26:29]
	v_mfma_f32_16x16x32_bf16 v[18:21], v[138:141], v[170:173], v[18:21]
	v_mfma_f32_16x16x32_bf16 v[10:13], v[130:133], v[162:165], v[10:13]
	v_mfma_f32_16x16x32_bf16 v[2:5], v[138:141], v[162:165], v[2:5]
	v_mfma_f32_16x16x32_bf16 v[58:61], v[134:137], v[190:193], v[58:61]
	v_mfma_f32_16x16x32_bf16 v[50:53], v[142:145], v[190:193], v[50:53]
	v_mfma_f32_16x16x32_bf16 v[42:45], v[134:137], v[182:185], v[42:45]
	v_mfma_f32_16x16x32_bf16 v[34:37], v[142:145], v[182:185], v[34:37]
	v_mfma_f32_16x16x32_bf16 v[26:29], v[134:137], v[174:177], v[26:29]
	v_mfma_f32_16x16x32_bf16 v[18:21], v[142:145], v[174:177], v[18:21]
	v_mfma_f32_16x16x32_bf16 v[10:13], v[134:137], v[166:169], v[10:13]
	v_mfma_f32_16x16x32_bf16 v[2:5], v[142:145], v[166:169], v[2:5]
	s_barrier
	s_add_i32 s65, s65, 2
	s_add_u32 s22, s22, 0x100
	s_addc_u32 s23, s23, 0
	s_add_u32 s13, s13, 0x100
	s_addc_u32 s15, s15, 0
	s_cmp_gt_u32 s65, 13
	s_cbranch_scc1 .LBB0_244

; #define PG8_STAGE(bufoff, gbase, voff) do { _Pragma("unroll") for (int _i = 0; _i < 2; ++_i) \
;         __builtin_amdgcn_global_load_lds((const unsigned*)((const char*)(gbase) + (voff)[_i]), (LAS unsigned*)(lds + (bufoff) + ldsw + _i * 8192), 16, 0, 0); } while (0)
; #define PG8_LDA(dst, b, h) do { _Pragma("unroll") for (int m = 0; m < 4; ++m) _Pragma("unroll") for (int k = 0; k < 2; ++k) dst[m][k] = *(const LAS bf16x8*)(lds + PG8_SA(b, h) + aoff + m * 2048 + k * 1024); } while (0)
; #define PG8_LDB(dst, b, h) do { _Pragma("unroll") for (int n = 0; n < 2; ++n) _Pragma("unroll") for (int k = 0; k < 2; ++k) dst[n][k] = *(const LAS bf16x8*)(lds + PG8_SB(b, h) + boff + n * 2048 + k * 1024); } while (0)
; #define PG8_MMA(ai, bj, At, Bt) do { __builtin_amdgcn_s_setprio(1); _Pragma("unroll") for (int m = 0; m < 4; ++m) _Pragma("unroll") for (int n = 0; n < 2; ++n) _Pragma("unroll") for (int k = 0; k < 2; ++k) \
;         acc[ai][bj][m][n] = __builtin_amdgcn_mfma_f32_16x16x32_bf16(Bt[n][k], At[m][k], acc[ai][bj][m][n], 0, 0, 0); __builtin_amdgcn_s_setprio(0); } while (0)
; #define PG8_WAIT_V(n) asm volatile("s_waitcnt vmcnt(" #n ")" ::: "memory")
; #define PG8_WAIT_L(n) asm volatile("s_waitcnt lgkmcnt(" #n ")" ::: "memory")
; #define PG8_BAR __builtin_amdgcn_s_barrier()
; #define PG8_SCHED __builtin_amdgcn_sched_barrier(0)
; template <class Epi, class Sched>
; __device__ __forceinline__ void gemm_phase(LAS unsigned char* lds, const int lda, const int ldb, const int K, const Sched& S, const Epi& E) {
;     ...
;             PG8_LDB(B0, 1, 0); PG8_LDB(B1, 1, 1); PG8_SCHED; PG8_LDA(At, 1, 0); PG8_STAGE(PG8_SA(0, 1), a2 + hstepA, voffA);
;             PG8_WAIT_V(8); PG8_WAIT_L(0); PG8_BAR; PG8_MMA(0, 0, At, B0); PG8_MMA(0, 1, At, B1); PG8_BAR; PG8_SCHED;
;             PG8_LDA(At, 1, 1); PG8_STAGE(PG8_SB(1, 0), b3, voffB); PG8_STAGE(PG8_SB(1, 1), b3 + hstepB, voffB); PG8_STAGE(PG8_SA(1, 0), a3, voffA);
;             PG8_WAIT_V(8); PG8_WAIT_L(0); PG8_BAR;
;             if (last) E.pre(cur, wr, fr, rsv);
;     __device__ __forceinline__ void pre(const pg8::Unit& u, int wr, int fr, float (&rsv)[8]) const {
;         const float* p = ss + u.pm * 256 + wr * 64 + fr;
; #pragma unroll
;         for (int ai = 0; ai < 2; ++ai)
; #pragma unroll
;             for (int m = 0; m < 4; ++m) rsv[ai * 4 + m] = p[ai * 128 + m * 16];
;     }
.Lpeel1_join:
	v_add_u32_e32 v130, s76, v195
	v_add_u32_e32 v142, s77, v195
	ds_read_b128 v[146:149], v130
	ds_read_b128 v[150:153], v130 offset:1024
	ds_read_b128 v[154:157], v130 offset:2048
	ds_read_b128 v[158:161], v130 offset:3072
	ds_read_b128 v[130:133], v142
	ds_read_b128 v[134:137], v142 offset:1024
	ds_read_b128 v[138:141], v142 offset:2048
	ds_read_b128 v[142:145], v142 offset:3072
	s_mov_b32 m0, s39
	ds_read_b128 v[162:165], v219 offset:32768
	ds_read_b128 v[166:169], v219 offset:33792
	ds_read_b128 v[170:173], v219 offset:34816
	ds_read_b128 v[174:177], v219 offset:35840
	ds_read_b128 v[178:181], v219 offset:36864
	ds_read_b128 v[182:185], v219 offset:37888
	ds_read_b128 v[186:189], v219 offset:38912
	ds_read_b128 v[190:193], v219 offset:39936
	global_load_lds_dwordx4 v202, s[26:27]
	s_mov_b32 m0, s40
	s_nop 0
	global_load_lds_dwordx4 v198, s[26:27]
	s_waitcnt vmcnt(8)
	s_waitcnt lgkmcnt(0)
	s_barrier
	v_mfma_f32_16x16x32_bf16 v[126:129], v[146:149], v[162:165], v[126:129]
	v_mfma_f32_16x16x32_bf16 v[118:121], v[154:157], v[162:165], v[118:121]
	v_mfma_f32_16x16x32_bf16 v[110:113], v[146:149], v[170:173], v[110:113]
	v_mfma_f32_16x16x32_bf16 v[102:105], v[154:157], v[170:173], v[102:105]
	v_mfma_f32_16x16x32_bf16 v[94:97], v[146:149], v[178:181], v[94:97]
	v_mfma_f32_16x16x32_bf16 v[86:89], v[154:157], v[178:181], v[86:89]
	v_mfma_f32_16x16x32_bf16 v[78:81], v[146:149], v[186:189], v[78:81]
	v_mfma_f32_16x16x32_bf16 v[70:73], v[154:157], v[186:189], v[70:73]
	v_mfma_f32_16x16x32_bf16 v[126:129], v[150:153], v[166:169], v[126:129]
	v_mfma_f32_16x16x32_bf16 v[118:121], v[158:161], v[166:169], v[118:121]
	v_mfma_f32_16x16x32_bf16 v[110:113], v[150:153], v[174:177], v[110:113]
	v_mfma_f32_16x16x32_bf16 v[102:105], v[158:161], v[174:177], v[102:105]
	v_mfma_f32_16x16x32_bf16 v[94:97], v[150:153], v[182:185], v[94:97]
	v_mfma_f32_16x16x32_bf16 v[86:89], v[158:161], v[182:185], v[86:89]
	v_mfma_f32_16x16x32_bf16 v[78:81], v[150:153], v[190:193], v[78:81]
	v_mfma_f32_16x16x32_bf16 v[70:73], v[158:161], v[190:193], v[70:73]
	v_mfma_f32_16x16x32_bf16 v[122:125], v[130:133], v[162:165], v[122:125]
	v_mfma_f32_16x16x32_bf16 v[114:117], v[138:141], v[162:165], v[114:117]
	v_mfma_f32_16x16x32_bf16 v[106:109], v[130:133], v[170:173], v[106:109]
	v_mfma_f32_16x16x32_bf16 v[98:101], v[138:141], v[170:173], v[98:101]
	v_mfma_f32_16x16x32_bf16 v[90:93], v[130:133], v[178:181], v[90:93]
	v_mfma_f32_16x16x32_bf16 v[82:85], v[138:141], v[178:181], v[82:85]
	v_mfma_f32_16x16x32_bf16 v[74:77], v[130:133], v[186:189], v[74:77]
	v_mfma_f32_16x16x32_bf16 v[66:69], v[138:141], v[186:189], v[66:69]
	v_mfma_f32_16x16x32_bf16 v[122:125], v[134:137], v[166:169], v[122:125]
	v_mfma_f32_16x16x32_bf16 v[114:117], v[142:145], v[166:169], v[114:117]
	v_mfma_f32_16x16x32_bf16 v[106:109], v[134:137], v[174:177], v[106:109]
	v_mfma_f32_16x16x32_bf16 v[98:101], v[142:145], v[174:177], v[98:101]
	v_mfma_f32_16x16x32_bf16 v[90:93], v[134:137], v[182:185], v[90:93]
	v_mfma_f32_16x16x32_bf16 v[82:85], v[142:145], v[182:185], v[82:85]
	v_mfma_f32_16x16x32_bf16 v[74:77], v[134:137], v[190:193], v[74:77]
	v_mfma_f32_16x16x32_bf16 v[66:69], v[142:145], v[190:193], v[66:69]
	s_barrier
	s_mov_b32 m0, s68
	ds_read_b128 v[186:189], v219 offset:49152
	ds_read_b128 v[190:193], v219 offset:50176
	ds_read_b128 v[178:181], v219 offset:51200
	ds_read_b128 v[182:185], v219 offset:52224
	ds_read_b128 v[170:173], v219 offset:53248
	ds_read_b128 v[174:177], v219 offset:54272
	ds_read_b128 v[162:165], v219 offset:55296
	ds_read_b128 v[166:169], v219 offset:56320
	global_load_lds_dwordx4 v230, s[30:31]
	s_mov_b32 m0, s21
	s_nop 0
	global_load_lds_dwordx4 v231, s[30:31]
	s_mov_b32 m0, s70
	s_nop 0
	global_load_lds_dwordx4 v200, s[24:25]
	s_mov_b32 m0, s69
	s_nop 0
	global_load_lds_dwordx4 v196, s[24:25]
	s_mov_b32 m0, s42
	s_nop 0
	global_load_lds_dwordx4 v232, s[28:29]
	s_mov_b32 m0, s43
	s_nop 0
	global_load_lds_dwordx4 v233, s[28:29]
	s_waitcnt vmcnt(8)
	s_waitcnt lgkmcnt(0)
	s_cbranch_scc1 .Lrot1
	s_barrier
	global_load_dword v228, v[214:215], off
	global_load_dword v227, v[214:215], off offset:64
	global_load_dword v226, v[214:215], off offset:128
	global_load_dword v225, v[214:215], off offset:192
	global_load_dword v224, v[214:215], off offset:512
	global_load_dword v223, v[214:215], off offset:576
	global_load_dword v222, v[214:215], off offset:640
	global_load_dword v221, v[214:215], off offset:704
	s_branch .LBB0_241

; #define PG8_STAGE(bufoff, gbase, voff) do { _Pragma("unroll") for (int _i = 0; _i < 2; ++_i) \
;         __builtin_amdgcn_global_load_lds((const unsigned*)((const char*)(gbase) + (voff)[_i]), (LAS unsigned*)(lds + (bufoff) + ldsw + _i * 8192), 16, 0, 0); } while (0)
; #define PG8_LDA(dst, b, h) do { _Pragma("unroll") for (int m = 0; m < 4; ++m) _Pragma("unroll") for (int k = 0; k < 2; ++k) dst[m][k] = *(const LAS bf16x8*)(lds + PG8_SA(b, h) + aoff + m * 2048 + k * 1024); } while (0)
; #define PG8_LDB(dst, b, h) do { _Pragma("unroll") for (int n = 0; n < 2; ++n) _Pragma("unroll") for (int k = 0; k < 2; ++k) dst[n][k] = *(const LAS bf16x8*)(lds + PG8_SB(b, h) + boff + n * 2048 + k * 1024); } while (0)
; #define PG8_MMA(ai, bj, At, Bt) do { __builtin_amdgcn_s_setprio(1); _Pragma("unroll") for (int m = 0; m < 4; ++m) _Pragma("unroll") for (int n = 0; n < 2; ++n) _Pragma("unroll") for (int k = 0; k < 2; ++k) \
;         acc[ai][bj][m][n] = __builtin_amdgcn_mfma_f32_16x16x32_bf16(Bt[n][k], At[m][k], acc[ai][bj][m][n], 0, 0, 0); __builtin_amdgcn_s_setprio(0); } while (0)
; #define PG8_WAIT_V(n) asm volatile("s_waitcnt vmcnt(" #n ")" ::: "memory")
; #define PG8_WAIT_L(n) asm volatile("s_waitcnt lgkmcnt(" #n ")" ::: "memory")
; #define PG8_BAR __builtin_amdgcn_s_barrier()
; #define PG8_SCHED __builtin_amdgcn_sched_barrier(0)
; template <class Epi, class Sched>
; __device__ __forceinline__ void gemm_phase(LAS unsigned char* lds, const int lda, const int ldb, const int K, const Sched& S, const Epi& E) {
;     ...
;         for (int t = 0; t < nt; t += 2) {
;             const bool last = (t == nt - 2);
;             const char* a1 = cA + (size_t)(t + 1) * kstep;
;             const char* a2 = last ? nA : cA + (size_t)(t + 2) * kstep; const char* b2 = last ? nB : cB + (size_t)(t + 2) * kstep;
;             const char* a3 = a2 + kstep; const char* b3 = b2 + kstep;
;             PG8_LDB(B0, 0, 0); PG8_LDB(B1, 0, 1); PG8_SCHED; PG8_LDA(At, 0, 0); PG8_STAGE(PG8_SA(1, 1), a1 + hstepA, voffA);
;             PG8_WAIT_V(8); PG8_WAIT_L(0); PG8_BAR; PG8_MMA(0, 0, At, B0); PG8_MMA(0, 1, At, B1); PG8_BAR; PG8_SCHED;
;             PG8_LDA(At, 0, 1); PG8_STAGE(PG8_SB(0, 0), b2, voffB); PG8_STAGE(PG8_SB(0, 1), b2 + hstepB, voffB); PG8_STAGE(PG8_SA(0, 0), a2, voffA);
;             PG8_WAIT_V(8); PG8_WAIT_L(0); PG8_BAR; PG8_MMA(1, 0, At, B0); PG8_MMA(1, 1, At, B1); PG8_BAR; PG8_SCHED;
.LBB0_424:
	s_lshl_b32 s4, s4, 8
	s_ashr_i32 s5, s4, 31
	s_add_u32 s6, s6, 0x40080
	s_addc_u32 s7, s7, 0
	v_lshl_add_u64 v[220:221], s[4:5], 2, v[206:207]
	s_add_u32 s5, s8, 0x100
	s_addc_u32 s51, s9, 0
	s_mov_b32 s69, -2
	v_add_u32_e32 v234, 0x80, v202
	v_add_u32_e32 v235, 0x80, v198
	v_add_u32_e32 v236, 0x80, v204
	v_add_u32_e32 v237, 0x80, v200
	s_add_u32 s8, s6, 0xfffc0080
	s_addc_u32 s9, s7, -1
	s_cmp_eq_u32 s69, 12
	s_cselect_b32 s13, s71, s9
	s_cselect_b32 s12, s70, s8
	s_cselect_b32 s15, s73, s51
	s_cselect_b32 s14, s72, s5
	s_add_i32 s81, s63, s36
	ds_read_b128 v[130:133], v222
	ds_read_b128 v[134:137], v222 offset:1024
	ds_read_b128 v[138:141], v222 offset:2048
	ds_read_b128 v[142:145], v222 offset:3072
	ds_read_b128 v[146:149], v223
	ds_read_b128 v[150:153], v223 offset:1024
	ds_read_b128 v[154:157], v223 offset:2048
	ds_read_b128 v[158:161], v223 offset:3072
	s_add_i32 m0, s39, 0xc000
	s_add_i32 s80, s39, 0xe000
	s_add_i32 s82, s81, 0x2000
	s_add_u32 s16, s14, 0x40000
	s_addc_u32 s17, s15, 0
	s_add_i32 s83, s64, s36
	s_add_i32 s84, s83, 0x2000
	s_add_i32 s85, 0, 0x18000
	s_add_i32 s86, 0, 0x1c000
	s_add_u32 s10, s12, 0x40000
	s_addc_u32 s11, s13, 0
	s_add_i32 s75, s85, s36
	s_add_i32 s74, s75, 0x2000
	s_add_u32 s8, s14, 0x40080
	s_addc_u32 s9, s15, 0
	s_add_i32 s79, s86, s36
	s_add_i32 s78, s79, 0x2000
	s_cmp_lg_u32 s69, 12
	ds_read_b128 v[162:165], v224
	ds_read_b128 v[166:169], v224 offset:1024
	ds_read_b128 v[170:173], v224 offset:2048
	ds_read_b128 v[174:177], v224 offset:3072
	ds_read_b128 v[178:181], v224 offset:4096
	ds_read_b128 v[182:185], v224 offset:5120
	ds_read_b128 v[186:189], v224 offset:6144
	ds_read_b128 v[190:193], v224 offset:7168
	global_load_lds_dwordx4 v212, s[6:7]
	s_mov_b32 m0, s80
	s_nop 0
	global_load_lds_dwordx4 v214, s[6:7]
	s_waitcnt vmcnt(8)
	s_waitcnt lgkmcnt(0)
	s_barrier
	v_mfma_f32_16x16x32_bf16 v[126:129], v[130:133], v[162:165], 0
	v_mfma_f32_16x16x32_bf16 v[118:121], v[138:141], v[162:165], 0
	v_mfma_f32_16x16x32_bf16 v[110:113], v[130:133], v[170:173], 0
	v_mfma_f32_16x16x32_bf16 v[102:105], v[138:141], v[170:173], 0
	v_mfma_f32_16x16x32_bf16 v[94:97], v[130:133], v[178:181], 0
	v_mfma_f32_16x16x32_bf16 v[86:89], v[138:141], v[178:181], 0
	v_mfma_f32_16x16x32_bf16 v[78:81], v[130:133], v[186:189], 0
	v_mfma_f32_16x16x32_bf16 v[70:73], v[138:141], v[186:189], 0
	v_mfma_f32_16x16x32_bf16 v[126:129], v[134:137], v[166:169], v[126:129]
	v_mfma_f32_16x16x32_bf16 v[118:121], v[142:145], v[166:169], v[118:121]
	v_mfma_f32_16x16x32_bf16 v[110:113], v[134:137], v[174:177], v[110:113]
	v_mfma_f32_16x16x32_bf16 v[102:105], v[142:145], v[174:177], v[102:105]
	v_mfma_f32_16x16x32_bf16 v[94:97], v[134:137], v[182:185], v[94:97]
	v_mfma_f32_16x16x32_bf16 v[86:89], v[142:145], v[182:185], v[86:89]
	v_mfma_f32_16x16x32_bf16 v[78:81], v[134:137], v[190:193], v[78:81]
	v_mfma_f32_16x16x32_bf16 v[70:73], v[142:145], v[190:193], v[70:73]
	v_mfma_f32_16x16x32_bf16 v[122:125], v[146:149], v[162:165], 0
	v_mfma_f32_16x16x32_bf16 v[114:117], v[154:157], v[162:165], 0
	v_mfma_f32_16x16x32_bf16 v[106:109], v[146:149], v[170:173], 0
	v_mfma_f32_16x16x32_bf16 v[98:101], v[154:157], v[170:173], 0
	v_mfma_f32_16x16x32_bf16 v[90:93], v[146:149], v[178:181], 0
	v_mfma_f32_16x16x32_bf16 v[82:85], v[154:157], v[178:181], 0
	v_mfma_f32_16x16x32_bf16 v[74:77], v[146:149], v[186:189], 0
	v_mfma_f32_16x16x32_bf16 v[66:69], v[154:157], v[186:189], 0
	v_mfma_f32_16x16x32_bf16 v[122:125], v[150:153], v[166:169], v[122:125]
	v_mfma_f32_16x16x32_bf16 v[114:117], v[158:161], v[166:169], v[114:117]
	v_mfma_f32_16x16x32_bf16 v[106:109], v[150:153], v[174:177], v[106:109]
	v_mfma_f32_16x16x32_bf16 v[98:101], v[158:161], v[174:177], v[98:101]
	v_mfma_f32_16x16x32_bf16 v[90:93], v[150:153], v[182:185], v[90:93]
	v_mfma_f32_16x16x32_bf16 v[82:85], v[158:161], v[182:185], v[82:85]
	v_mfma_f32_16x16x32_bf16 v[74:77], v[150:153], v[190:193], v[74:77]
	v_mfma_f32_16x16x32_bf16 v[66:69], v[158:161], v[190:193], v[66:69]
	s_barrier
	s_mov_b32 m0, s81
	ds_read_b128 v[162:165], v224 offset:16384
	ds_read_b128 v[166:169], v224 offset:17408
	ds_read_b128 v[170:173], v224 offset:18432
	ds_read_b128 v[174:177], v224 offset:19456
	ds_read_b128 v[178:181], v224 offset:20480
	ds_read_b128 v[182:185], v224 offset:21504
	ds_read_b128 v[186:189], v224 offset:22528
	ds_read_b128 v[190:193], v224 offset:23552
	global_load_lds_dwordx4 v202, s[14:15]
	s_mov_b32 m0, s82
	s_nop 0
	global_load_lds_dwordx4 v198, s[14:15]
	s_mov_b32 m0, s83
	s_nop 0
	global_load_lds_dwordx4 v202, s[16:17]
	s_mov_b32 m0, s84
	s_nop 0
	global_load_lds_dwordx4 v198, s[16:17]
	s_mov_b32 m0, s39
	s_nop 0
	global_load_lds_dwordx4 v204, s[12:13]
	s_mov_b32 m0, s40
	s_nop 0
	global_load_lds_dwordx4 v200, s[12:13]
	s_waitcnt vmcnt(8)
	s_waitcnt lgkmcnt(0)
	s_barrier
	v_mfma_f32_16x16x32_bf16 v[62:65], v[130:133], v[162:165], 0
	v_mfma_f32_16x16x32_bf16 v[54:57], v[138:141], v[162:165], 0
	v_mfma_f32_16x16x32_bf16 v[46:49], v[130:133], v[170:173], 0
	v_mfma_f32_16x16x32_bf16 v[38:41], v[138:141], v[170:173], 0
	v_mfma_f32_16x16x32_bf16 v[30:33], v[130:133], v[178:181], 0
	v_mfma_f32_16x16x32_bf16 v[22:25], v[138:141], v[178:181], 0
	v_mfma_f32_16x16x32_bf16 v[14:17], v[130:133], v[186:189], 0
	v_mfma_f32_16x16x32_bf16 v[6:9], v[138:141], v[186:189], 0
	v_mfma_f32_16x16x32_bf16 v[62:65], v[134:137], v[166:169], v[62:65]
	v_mfma_f32_16x16x32_bf16 v[54:57], v[142:145], v[166:169], v[54:57]
	v_mfma_f32_16x16x32_bf16 v[46:49], v[134:137], v[174:177], v[46:49]
	v_mfma_f32_16x16x32_bf16 v[38:41], v[142:145], v[174:177], v[38:41]
	v_mfma_f32_16x16x32_bf16 v[30:33], v[134:137], v[182:185], v[30:33]
	v_mfma_f32_16x16x32_bf16 v[22:25], v[142:145], v[182:185], v[22:25]
	v_mfma_f32_16x16x32_bf16 v[14:17], v[134:137], v[190:193], v[14:17]
	v_mfma_f32_16x16x32_bf16 v[6:9], v[142:145], v[190:193], v[6:9]
	v_mfma_f32_16x16x32_bf16 v[58:61], v[146:149], v[162:165], 0
	v_mfma_f32_16x16x32_bf16 v[50:53], v[154:157], v[162:165], 0
	v_mfma_f32_16x16x32_bf16 v[42:45], v[146:149], v[170:173], 0
	v_mfma_f32_16x16x32_bf16 v[34:37], v[154:157], v[170:173], 0
	v_mfma_f32_16x16x32_bf16 v[26:29], v[146:149], v[178:181], 0
	v_mfma_f32_16x16x32_bf16 v[18:21], v[154:157], v[178:181], 0
	v_mfma_f32_16x16x32_bf16 v[10:13], v[146:149], v[186:189], 0
	v_mfma_f32_16x16x32_bf16 v[2:5], v[154:157], v[186:189], 0
	v_mfma_f32_16x16x32_bf16 v[58:61], v[150:153], v[166:169], v[58:61]
	v_mfma_f32_16x16x32_bf16 v[50:53], v[158:161], v[166:169], v[50:53]
	v_mfma_f32_16x16x32_bf16 v[42:45], v[150:153], v[174:177], v[42:45]
	v_mfma_f32_16x16x32_bf16 v[34:37], v[158:161], v[174:177], v[34:37]
	v_mfma_f32_16x16x32_bf16 v[26:29], v[150:153], v[182:185], v[26:29]
	v_mfma_f32_16x16x32_bf16 v[18:21], v[158:161], v[182:185], v[18:21]
	v_mfma_f32_16x16x32_bf16 v[10:13], v[150:153], v[190:193], v[10:13]
	v_mfma_f32_16x16x32_bf16 v[2:5], v[158:161], v[190:193], v[2:5]
	s_barrier
	s_branch .Lpeel3_join
; #define PG8_MMA(ai, bj, At, Bt) do { __builtin_amdgcn_s_setprio(1); _Pragma("unroll") for (int m = 0; m < 4; ++m) _Pragma("unroll") for (int n = 0; n < 2; ++n) _Pragma("unroll") for (int k = 0; k < 2; ++k) \
;         acc[ai][bj][m][n] = __builtin_amdgcn_mfma_f32_16x16x32_bf16(Bt[n][k], At[m][k], acc[ai][bj][m][n], 0, 0, 0); __builtin_amdgcn_s_setprio(0); } while (0)
; #define PG8_WAIT_V(n) asm volatile("s_waitcnt vmcnt(" #n ")" ::: "memory")
; #define PG8_WAIT_L(n) asm volatile("s_waitcnt lgkmcnt(" #n ")" ::: "memory")
; #define PG8_BAR __builtin_amdgcn_s_barrier()
; #define PG8_SCHED __builtin_amdgcn_sched_barrier(0)
; template <class Epi, class Sched>
; __device__ __forceinline__ void gemm_phase(LAS unsigned char* lds, const int lda, const int ldb, const int K, const Sched& S, const Epi& E) {
;     ...
;             PG8_WAIT_V(8); PG8_WAIT_L(0); PG8_BAR;
;             if (last) E.pre(cur, wr, fr, rsv);
;             PG8_MMA(1, 0, At, B0); PG8_MMA(1, 1, At, B1); PG8_BAR; PG8_SCHED;
;         }
.Lrot3:
	s_barrier
.LBB0_425:
	v_mfma_f32_16x16x32_bf16 v[62:65], v[146:149], v[186:189], v[62:65]
	v_mfma_f32_16x16x32_bf16 v[54:57], v[154:157], v[186:189], v[54:57]
	v_mfma_f32_16x16x32_bf16 v[46:49], v[146:149], v[178:181], v[46:49]
	v_mfma_f32_16x16x32_bf16 v[38:41], v[154:157], v[178:181], v[38:41]
	v_mfma_f32_16x16x32_bf16 v[30:33], v[146:149], v[170:173], v[30:33]
	v_mfma_f32_16x16x32_bf16 v[22:25], v[154:157], v[170:173], v[22:25]
	v_mfma_f32_16x16x32_bf16 v[14:17], v[146:149], v[162:165], v[14:17]
	v_mfma_f32_16x16x32_bf16 v[6:9], v[154:157], v[162:165], v[6:9]
	v_mfma_f32_16x16x32_bf16 v[62:65], v[150:153], v[190:193], v[62:65]
	v_mfma_f32_16x16x32_bf16 v[54:57], v[158:161], v[190:193], v[54:57]
	v_mfma_f32_16x16x32_bf16 v[46:49], v[150:153], v[182:185], v[46:49]
	v_mfma_f32_16x16x32_bf16 v[38:41], v[158:161], v[182:185], v[38:41]
	v_mfma_f32_16x16x32_bf16 v[30:33], v[150:153], v[174:177], v[30:33]
	v_mfma_f32_16x16x32_bf16 v[22:25], v[158:161], v[174:177], v[22:25]
	v_mfma_f32_16x16x32_bf16 v[14:17], v[150:153], v[166:169], v[14:17]
	v_mfma_f32_16x16x32_bf16 v[6:9], v[158:161], v[166:169], v[6:9]
	v_mfma_f32_16x16x32_bf16 v[58:61], v[130:133], v[186:189], v[58:61]
	v_mfma_f32_16x16x32_bf16 v[50:53], v[138:141], v[186:189], v[50:53]
	v_mfma_f32_16x16x32_bf16 v[42:45], v[130:133], v[178:181], v[42:45]
	v_mfma_f32_16x16x32_bf16 v[34:37], v[138:141], v[178:181], v[34:37]
	v_mfma_f32_16x16x32_bf16 v[26:29], v[130:133], v[170:173], v[26:29]
	v_mfma_f32_16x16x32_bf16 v[18:21], v[138:141], v[170:173], v[18:21]
	v_mfma_f32_16x16x32_bf16 v[10:13], v[130:133], v[162:165], v[10:13]
	v_mfma_f32_16x16x32_bf16 v[2:5], v[138:141], v[162:165], v[2:5]
	v_mfma_f32_16x16x32_bf16 v[58:61], v[134:137], v[190:193], v[58:61]
	v_mfma_f32_16x16x32_bf16 v[50:53], v[142:145], v[190:193], v[50:53]
	v_mfma_f32_16x16x32_bf16 v[42:45], v[134:137], v[182:185], v[42:45]
	v_mfma_f32_16x16x32_bf16 v[34:37], v[142:145], v[182:185], v[34:37]
	v_mfma_f32_16x16x32_bf16 v[26:29], v[134:137], v[174:177], v[26:29]
	v_mfma_f32_16x16x32_bf16 v[18:21], v[142:145], v[174:177], v[18:21]
	v_mfma_f32_16x16x32_bf16 v[10:13], v[134:137], v[166:169], v[10:13]
	v_mfma_f32_16x16x32_bf16 v[2:5], v[142:145], v[166:169], v[2:5]
	s_barrier
	s_add_i32 s69, s69, 2
	s_add_u32 s6, s6, 0x100
	s_addc_u32 s7, s7, 0
	s_add_u32 s5, s5, 0x100
	s_addc_u32 s51, s51, 0
	s_cmp_gt_u32 s69, 13
	s_cbranch_scc1 .LBB0_428

; #define PG8_STAGE(bufoff, gbase, voff) do { _Pragma("unroll") for (int _i = 0; _i < 2; ++_i) \
;         __builtin_amdgcn_global_load_lds((const unsigned*)((const char*)(gbase) + (voff)[_i]), (LAS unsigned*)(lds + (bufoff) + ldsw + _i * 8192), 16, 0, 0); } while (0)
; #define PG8_LDA(dst, b, h) do { _Pragma("unroll") for (int m = 0; m < 4; ++m) _Pragma("unroll") for (int k = 0; k < 2; ++k) dst[m][k] = *(const LAS bf16x8*)(lds + PG8_SA(b, h) + aoff + m * 2048 + k * 1024); } while (0)
; #define PG8_LDB(dst, b, h) do { _Pragma("unroll") for (int n = 0; n < 2; ++n) _Pragma("unroll") for (int k = 0; k < 2; ++k) dst[n][k] = *(const LAS bf16x8*)(lds + PG8_SB(b, h) + boff + n * 2048 + k * 1024); } while (0)
; #define PG8_MMA(ai, bj, At, Bt) do { __builtin_amdgcn_s_setprio(1); _Pragma("unroll") for (int m = 0; m < 4; ++m) _Pragma("unroll") for (int n = 0; n < 2; ++n) _Pragma("unroll") for (int k = 0; k < 2; ++k) \
;         acc[ai][bj][m][n] = __builtin_amdgcn_mfma_f32_16x16x32_bf16(Bt[n][k], At[m][k], acc[ai][bj][m][n], 0, 0, 0); __builtin_amdgcn_s_setprio(0); } while (0)
; #define PG8_WAIT_V(n) asm volatile("s_waitcnt vmcnt(" #n ")" ::: "memory")
; #define PG8_WAIT_L(n) asm volatile("s_waitcnt lgkmcnt(" #n ")" ::: "memory")
; #define PG8_BAR __builtin_amdgcn_s_barrier()
; #define PG8_SCHED __builtin_amdgcn_sched_barrier(0)
; template <class Epi, class Sched>
; __device__ __forceinline__ void gemm_phase(LAS unsigned char* lds, const int lda, const int ldb, const int K, const Sched& S, const Epi& E) {
;     ...
;             PG8_LDB(B0, 1, 0); PG8_LDB(B1, 1, 1); PG8_SCHED; PG8_LDA(At, 1, 0); PG8_STAGE(PG8_SA(0, 1), a2 + hstepA, voffA);
;             PG8_WAIT_V(8); PG8_WAIT_L(0); PG8_BAR; PG8_MMA(0, 0, At, B0); PG8_MMA(0, 1, At, B1); PG8_BAR; PG8_SCHED;
;             PG8_LDA(At, 1, 1); PG8_STAGE(PG8_SB(1, 0), b3, voffB); PG8_STAGE(PG8_SB(1, 1), b3 + hstepB, voffB); PG8_STAGE(PG8_SA(1, 0), a3, voffA);
;             PG8_WAIT_V(8); PG8_WAIT_L(0); PG8_BAR;
;             if (last) E.pre(cur, wr, fr, rsv);
;     __device__ __forceinline__ void pre(const pg8::Unit& u, int wr, int fr, float (&rsv)[8]) const {
;         const float* p = ss + u.pm * 256 + wr * 64 + fr;
; #pragma unroll
;         for (int ai = 0; ai < 2; ++ai)
; #pragma unroll
;             for (int m = 0; m < 4; ++m) rsv[ai * 4 + m] = p[ai * 128 + m * 16];
;     }
.Lpeel3_join:
	v_add_u32_e32 v130, s85, v195
	v_add_u32_e32 v142, s86, v195
	ds_read_b128 v[146:149], v130
	ds_read_b128 v[150:153], v130 offset:1024
	ds_read_b128 v[154:157], v130 offset:2048
	ds_read_b128 v[158:161], v130 offset:3072
	ds_read_b128 v[130:133], v142
	ds_read_b128 v[134:137], v142 offset:1024
	ds_read_b128 v[138:141], v142 offset:2048
	ds_read_b128 v[142:145], v142 offset:3072
	s_mov_b32 m0, s41
	ds_read_b128 v[162:165], v224 offset:32768
	ds_read_b128 v[166:169], v224 offset:33792
	ds_read_b128 v[170:173], v224 offset:34816
	ds_read_b128 v[174:177], v224 offset:35840
	ds_read_b128 v[178:181], v224 offset:36864
	ds_read_b128 v[182:185], v224 offset:37888
	ds_read_b128 v[186:189], v224 offset:38912
	ds_read_b128 v[190:193], v224 offset:39936
	global_load_lds_dwordx4 v204, s[10:11]
	s_mov_b32 m0, s42
	s_nop 0
	global_load_lds_dwordx4 v200, s[10:11]
	s_waitcnt vmcnt(8)
	s_waitcnt lgkmcnt(0)
	s_barrier
	v_mfma_f32_16x16x32_bf16 v[126:129], v[146:149], v[162:165], v[126:129]
	v_mfma_f32_16x16x32_bf16 v[118:121], v[154:157], v[162:165], v[118:121]
	v_mfma_f32_16x16x32_bf16 v[110:113], v[146:149], v[170:173], v[110:113]
	v_mfma_f32_16x16x32_bf16 v[102:105], v[154:157], v[170:173], v[102:105]
	v_mfma_f32_16x16x32_bf16 v[94:97], v[146:149], v[178:181], v[94:97]
	v_mfma_f32_16x16x32_bf16 v[86:89], v[154:157], v[178:181], v[86:89]
	v_mfma_f32_16x16x32_bf16 v[78:81], v[146:149], v[186:189], v[78:81]
	v_mfma_f32_16x16x32_bf16 v[70:73], v[154:157], v[186:189], v[70:73]
	v_mfma_f32_16x16x32_bf16 v[126:129], v[150:153], v[166:169], v[126:129]
	v_mfma_f32_16x16x32_bf16 v[118:121], v[158:161], v[166:169], v[118:121]
	v_mfma_f32_16x16x32_bf16 v[110:113], v[150:153], v[174:177], v[110:113]
	v_mfma_f32_16x16x32_bf16 v[102:105], v[158:161], v[174:177], v[102:105]
	v_mfma_f32_16x16x32_bf16 v[94:97], v[150:153], v[182:185], v[94:97]
	v_mfma_f32_16x16x32_bf16 v[86:89], v[158:161], v[182:185], v[86:89]
	v_mfma_f32_16x16x32_bf16 v[78:81], v[150:153], v[190:193], v[78:81]
	v_mfma_f32_16x16x32_bf16 v[70:73], v[158:161], v[190:193], v[70:73]
	v_mfma_f32_16x16x32_bf16 v[122:125], v[130:133], v[162:165], v[122:125]
	v_mfma_f32_16x16x32_bf16 v[114:117], v[138:141], v[162:165], v[114:117]
	v_mfma_f32_16x16x32_bf16 v[106:109], v[130:133], v[170:173], v[106:109]
	v_mfma_f32_16x16x32_bf16 v[98:101], v[138:141], v[170:173], v[98:101]
	v_mfma_f32_16x16x32_bf16 v[90:93], v[130:133], v[178:181], v[90:93]
	v_mfma_f32_16x16x32_bf16 v[82:85], v[138:141], v[178:181], v[82:85]
	v_mfma_f32_16x16x32_bf16 v[74:77], v[130:133], v[186:189], v[74:77]
	v_mfma_f32_16x16x32_bf16 v[66:69], v[138:141], v[186:189], v[66:69]
	v_mfma_f32_16x16x32_bf16 v[122:125], v[134:137], v[166:169], v[122:125]
	v_mfma_f32_16x16x32_bf16 v[114:117], v[142:145], v[166:169], v[114:117]
	v_mfma_f32_16x16x32_bf16 v[106:109], v[134:137], v[174:177], v[106:109]
	v_mfma_f32_16x16x32_bf16 v[98:101], v[142:145], v[174:177], v[98:101]
	v_mfma_f32_16x16x32_bf16 v[90:93], v[134:137], v[182:185], v[90:93]
	v_mfma_f32_16x16x32_bf16 v[82:85], v[142:145], v[182:185], v[82:85]
	v_mfma_f32_16x16x32_bf16 v[74:77], v[134:137], v[190:193], v[74:77]
	v_mfma_f32_16x16x32_bf16 v[66:69], v[142:145], v[190:193], v[66:69]
	s_barrier
	s_mov_b32 m0, s75
	ds_read_b128 v[186:189], v224 offset:49152
	ds_read_b128 v[190:193], v224 offset:50176
	ds_read_b128 v[178:181], v224 offset:51200
	ds_read_b128 v[182:185], v224 offset:52224
	ds_read_b128 v[170:173], v224 offset:53248
	ds_read_b128 v[174:177], v224 offset:54272
	ds_read_b128 v[162:165], v224 offset:55296
	ds_read_b128 v[166:169], v224 offset:56320
	global_load_lds_dwordx4 v234, s[14:15]
	s_mov_b32 m0, s74
	s_nop 0
	global_load_lds_dwordx4 v235, s[14:15]
	s_mov_b32 m0, s79
	s_nop 0
	global_load_lds_dwordx4 v202, s[8:9]
	s_mov_b32 m0, s78
	s_nop 0
	global_load_lds_dwordx4 v198, s[8:9]
	s_mov_b32 m0, s43
	s_nop 0
	global_load_lds_dwordx4 v236, s[12:13]
	s_mov_b32 m0, s44
	s_nop 0
	global_load_lds_dwordx4 v237, s[12:13]
	s_waitcnt vmcnt(8)
	s_waitcnt lgkmcnt(0)
	s_cbranch_scc1 .Lrot3
	s_barrier
	global_load_dword v233, v[220:221], off
	global_load_dword v232, v[220:221], off offset:64
	global_load_dword v231, v[220:221], off offset:128
	global_load_dword v230, v[220:221], off offset:192
	global_load_dword v229, v[220:221], off offset:512
	global_load_dword v228, v[220:221], off offset:576
	global_load_dword v227, v[220:221], off offset:640
	global_load_dword v226, v[220:221], off offset:704
	s_branch .LBB0_425

; #define PG8_STAGE(bufoff, gbase, voff) do { _Pragma("unroll") for (int _i = 0; _i < 2; ++_i) \
;         __builtin_amdgcn_global_load_lds((const unsigned*)((const char*)(gbase) + (voff)[_i]), (LAS unsigned*)(lds + (bufoff) + ldsw + _i * 8192), 16, 0, 0); } while (0)
; #define PG8_LDA(dst, b, h) do { _Pragma("unroll") for (int m = 0; m < 4; ++m) _Pragma("unroll") for (int k = 0; k < 2; ++k) dst[m][k] = *(const LAS bf16x8*)(lds + PG8_SA(b, h) + aoff + m * 2048 + k * 1024); } while (0)
; #define PG8_LDB(dst, b, h) do { _Pragma("unroll") for (int n = 0; n < 2; ++n) _Pragma("unroll") for (int k = 0; k < 2; ++k) dst[n][k] = *(const LAS bf16x8*)(lds + PG8_SB(b, h) + boff + n * 2048 + k * 1024); } while (0)
; #define PG8_MMA(ai, bj, At, Bt) do { __builtin_amdgcn_s_setprio(1); _Pragma("unroll") for (int m = 0; m < 4; ++m) _Pragma("unroll") for (int n = 0; n < 2; ++n) _Pragma("unroll") for (int k = 0; k < 2; ++k) \
;         acc[ai][bj][m][n] = __builtin_amdgcn_mfma_f32_16x16x32_bf16(Bt[n][k], At[m][k], acc[ai][bj][m][n], 0, 0, 0); __builtin_amdgcn_s_setprio(0); } while (0)
; #define PG8_WAIT_V(n) asm volatile("s_waitcnt vmcnt(" #n ")" ::: "memory")
; #define PG8_WAIT_L(n) asm volatile("s_waitcnt lgkmcnt(" #n ")" ::: "memory")
; #define PG8_BAR __builtin_amdgcn_s_barrier()
; #define PG8_SCHED __builtin_amdgcn_sched_barrier(0)
; template <class Epi, class Sched>
; __device__ __forceinline__ void gemm_phase(LAS unsigned char* lds, const int lda, const int ldb, const int K, const Sched& S, const Epi& E) {
;     ...
;         for (int t = 0; t < nt; t += 2) {
;             const bool last = (t == nt - 2);
;             const char* a1 = cA + (size_t)(t + 1) * kstep;
;             const char* a2 = last ? nA : cA + (size_t)(t + 2) * kstep; const char* b2 = last ? nB : cB + (size_t)(t + 2) * kstep;
;             const char* a3 = a2 + kstep; const char* b3 = b2 + kstep;
;             PG8_LDB(B0, 0, 0); PG8_LDB(B1, 0, 1); PG8_SCHED; PG8_LDA(At, 0, 0); PG8_STAGE(PG8_SA(1, 1), a1 + hstepA, voffA);
;             PG8_WAIT_V(8); PG8_WAIT_L(0); PG8_BAR; PG8_MMA(0, 0, At, B0); PG8_MMA(0, 1, At, B1); PG8_BAR; PG8_SCHED;
;             PG8_LDA(At, 0, 1); PG8_STAGE(PG8_SB(0, 0), b2, voffB); PG8_STAGE(PG8_SB(0, 1), b2 + hstepB, voffB); PG8_STAGE(PG8_SA(0, 0), a2, voffA);
;             PG8_WAIT_V(8); PG8_WAIT_L(0); PG8_BAR; PG8_MMA(1, 0, At, B0); PG8_MMA(1, 1, At, B1); PG8_BAR; PG8_SCHED;
.LBB0_1052:
	s_lshl_b32 s20, s20, 8
	s_ashr_i32 s21, s20, 31
	s_add_u32 s22, s22, 0x40080
	s_addc_u32 s23, s23, 0
	s_add_u32 s13, s24, 0x100
	v_lshl_add_u64 v[214:215], s[20:21], 2, v[204:205]
	s_addc_u32 s15, s25, 0
	s_mov_b32 s21, -2
	v_add_u32_e32 v230, 0x80, v200
	v_add_u32_e32 v231, 0x80, v196
	v_add_u32_e32 v232, 0x80, v202
	v_add_u32_e32 v233, 0x80, v198
	s_add_u32 s24, s22, 0xfffc0080
	s_addc_u32 s25, s23, -1
	s_cmp_eq_u32 s21, 12
	s_cselect_b32 s29, s17, s25
	s_cselect_b32 s28, s16, s24
	s_cselect_b32 s31, s19, s15
	s_cselect_b32 s30, s18, s13
	s_add_i32 s70, s50, s36
	s_add_i32 m0, s39, 0xc000
	s_add_i32 s69, s39, 0xe000
	s_add_i32 s71, s70, 0x2000
	s_add_u32 s34, s30, 0x40000
	s_addc_u32 s35, s31, 0
	s_add_i32 s72, s51, s36
	s_add_i32 s73, s72, 0x2000
	s_add_i32 s74, 0, 0x18000
	s_add_i32 s75, 0, 0x1c000
	s_add_u32 s26, s28, 0x40000
	s_addc_u32 s27, s29, 0
	s_add_i32 s66, s74, s36
	s_add_i32 s65, s66, 0x2000
	s_add_u32 s24, s30, 0x40080
	s_addc_u32 s25, s31, 0
	s_add_i32 s68, s75, s36
	s_add_i32 s67, s68, 0x2000
	s_cmp_lg_u32 s21, 12
	global_load_lds_dwordx4 v206, s[22:23]
	s_mov_b32 m0, s69
	s_nop 0
	global_load_lds_dwordx4 v208, s[22:23]
	s_waitcnt vmcnt(8)
	s_waitcnt lgkmcnt(0)
	s_barrier
	v_mfma_f32_16x16x32_bf16 v[126:129], v[130:133], v[162:165], 0
	v_mfma_f32_16x16x32_bf16 v[118:121], v[138:141], v[162:165], 0
	v_mfma_f32_16x16x32_bf16 v[110:113], v[130:133], v[170:173], 0
	v_mfma_f32_16x16x32_bf16 v[102:105], v[138:141], v[170:173], 0
	v_mfma_f32_16x16x32_bf16 v[94:97], v[130:133], v[178:181], 0
	v_mfma_f32_16x16x32_bf16 v[86:89], v[138:141], v[178:181], 0
	v_mfma_f32_16x16x32_bf16 v[78:81], v[130:133], v[186:189], 0
	v_mfma_f32_16x16x32_bf16 v[70:73], v[138:141], v[186:189], 0
	v_mfma_f32_16x16x32_bf16 v[126:129], v[134:137], v[166:169], v[126:129]
	v_mfma_f32_16x16x32_bf16 v[118:121], v[142:145], v[166:169], v[118:121]
	v_mfma_f32_16x16x32_bf16 v[110:113], v[134:137], v[174:177], v[110:113]
	v_mfma_f32_16x16x32_bf16 v[102:105], v[142:145], v[174:177], v[102:105]
	v_mfma_f32_16x16x32_bf16 v[94:97], v[134:137], v[182:185], v[94:97]
	v_mfma_f32_16x16x32_bf16 v[86:89], v[142:145], v[182:185], v[86:89]
	v_mfma_f32_16x16x32_bf16 v[78:81], v[134:137], v[190:193], v[78:81]
	v_mfma_f32_16x16x32_bf16 v[70:73], v[142:145], v[190:193], v[70:73]
	v_mfma_f32_16x16x32_bf16 v[122:125], v[146:149], v[162:165], 0
	v_mfma_f32_16x16x32_bf16 v[114:117], v[154:157], v[162:165], 0
	v_mfma_f32_16x16x32_bf16 v[106:109], v[146:149], v[170:173], 0
	v_mfma_f32_16x16x32_bf16 v[98:101], v[154:157], v[170:173], 0
	v_mfma_f32_16x16x32_bf16 v[90:93], v[146:149], v[178:181], 0
	v_mfma_f32_16x16x32_bf16 v[82:85], v[154:157], v[178:181], 0
	v_mfma_f32_16x16x32_bf16 v[74:77], v[146:149], v[186:189], 0
	v_mfma_f32_16x16x32_bf16 v[66:69], v[154:157], v[186:189], 0
	v_mfma_f32_16x16x32_bf16 v[122:125], v[150:153], v[166:169], v[122:125]
	v_mfma_f32_16x16x32_bf16 v[114:117], v[158:161], v[166:169], v[114:117]
	v_mfma_f32_16x16x32_bf16 v[106:109], v[150:153], v[174:177], v[106:109]
	v_mfma_f32_16x16x32_bf16 v[98:101], v[158:161], v[174:177], v[98:101]
	v_mfma_f32_16x16x32_bf16 v[90:93], v[150:153], v[182:185], v[90:93]
	v_mfma_f32_16x16x32_bf16 v[82:85], v[158:161], v[182:185], v[82:85]
	v_mfma_f32_16x16x32_bf16 v[74:77], v[150:153], v[190:193], v[74:77]
	v_mfma_f32_16x16x32_bf16 v[66:69], v[158:161], v[190:193], v[66:69]
	s_barrier
	s_mov_b32 m0, s70
	ds_read_b128 v[162:165], v219 offset:16384
	ds_read_b128 v[166:169], v219 offset:17408
	ds_read_b128 v[170:173], v219 offset:18432
	ds_read_b128 v[174:177], v219 offset:19456
	ds_read_b128 v[178:181], v219 offset:20480
	ds_read_b128 v[182:185], v219 offset:21504
	ds_read_b128 v[186:189], v219 offset:22528
	ds_read_b128 v[190:193], v219 offset:23552
	global_load_lds_dwordx4 v200, s[30:31]
	s_mov_b32 m0, s71
	s_nop 0
	global_load_lds_dwordx4 v196, s[30:31]
	s_mov_b32 m0, s72
	s_nop 0
	global_load_lds_dwordx4 v200, s[34:35]
	s_mov_b32 m0, s73
	s_nop 0
	global_load_lds_dwordx4 v196, s[34:35]
	s_mov_b32 m0, s39
	s_nop 0
	global_load_lds_dwordx4 v202, s[28:29]
	s_mov_b32 m0, s40
	s_nop 0
	global_load_lds_dwordx4 v198, s[28:29]
	s_waitcnt vmcnt(8)
	s_waitcnt lgkmcnt(0)
	s_barrier
	v_mfma_f32_16x16x32_bf16 v[62:65], v[130:133], v[162:165], 0
	v_mfma_f32_16x16x32_bf16 v[54:57], v[138:141], v[162:165], 0
	v_mfma_f32_16x16x32_bf16 v[46:49], v[130:133], v[170:173], 0
	v_mfma_f32_16x16x32_bf16 v[38:41], v[138:141], v[170:173], 0
	v_mfma_f32_16x16x32_bf16 v[30:33], v[130:133], v[178:181], 0
	v_mfma_f32_16x16x32_bf16 v[22:25], v[138:141], v[178:181], 0
	v_mfma_f32_16x16x32_bf16 v[14:17], v[130:133], v[186:189], 0
	v_mfma_f32_16x16x32_bf16 v[6:9], v[138:141], v[186:189], 0
	v_mfma_f32_16x16x32_bf16 v[62:65], v[134:137], v[166:169], v[62:65]
	v_mfma_f32_16x16x32_bf16 v[54:57], v[142:145], v[166:169], v[54:57]
	v_mfma_f32_16x16x32_bf16 v[46:49], v[134:137], v[174:177], v[46:49]
	v_mfma_f32_16x16x32_bf16 v[38:41], v[142:145], v[174:177], v[38:41]
	v_mfma_f32_16x16x32_bf16 v[30:33], v[134:137], v[182:185], v[30:33]
	v_mfma_f32_16x16x32_bf16 v[22:25], v[142:145], v[182:185], v[22:25]
	v_mfma_f32_16x16x32_bf16 v[14:17], v[134:137], v[190:193], v[14:17]
	v_mfma_f32_16x16x32_bf16 v[6:9], v[142:145], v[190:193], v[6:9]
	v_mfma_f32_16x16x32_bf16 v[58:61], v[146:149], v[162:165], 0
	v_mfma_f32_16x16x32_bf16 v[50:53], v[154:157], v[162:165], 0
	v_mfma_f32_16x16x32_bf16 v[42:45], v[146:149], v[170:173], 0
	v_mfma_f32_16x16x32_bf16 v[34:37], v[154:157], v[170:173], 0
	v_mfma_f32_16x16x32_bf16 v[26:29], v[146:149], v[178:181], 0
	v_mfma_f32_16x16x32_bf16 v[18:21], v[154:157], v[178:181], 0
	v_mfma_f32_16x16x32_bf16 v[10:13], v[146:149], v[186:189], 0
	v_mfma_f32_16x16x32_bf16 v[2:5], v[154:157], v[186:189], 0
	v_mfma_f32_16x16x32_bf16 v[58:61], v[150:153], v[166:169], v[58:61]
	v_mfma_f32_16x16x32_bf16 v[50:53], v[158:161], v[166:169], v[50:53]
	v_mfma_f32_16x16x32_bf16 v[42:45], v[150:153], v[174:177], v[42:45]
	v_mfma_f32_16x16x32_bf16 v[34:37], v[158:161], v[174:177], v[34:37]
	v_mfma_f32_16x16x32_bf16 v[26:29], v[150:153], v[182:185], v[26:29]
	v_mfma_f32_16x16x32_bf16 v[18:21], v[158:161], v[182:185], v[18:21]
	v_mfma_f32_16x16x32_bf16 v[10:13], v[150:153], v[190:193], v[10:13]
	v_mfma_f32_16x16x32_bf16 v[2:5], v[158:161], v[190:193], v[2:5]
	s_barrier
	s_branch .Lpeel6_join
; #define PG8_MMA(ai, bj, At, Bt) do { __builtin_amdgcn_s_setprio(1); _Pragma("unroll") for (int m = 0; m < 4; ++m) _Pragma("unroll") for (int n = 0; n < 2; ++n) _Pragma("unroll") for (int k = 0; k < 2; ++k) \
;         acc[ai][bj][m][n] = __builtin_amdgcn_mfma_f32_16x16x32_bf16(Bt[n][k], At[m][k], acc[ai][bj][m][n], 0, 0, 0); __builtin_amdgcn_s_setprio(0); } while (0)
; #define PG8_WAIT_V(n) asm volatile("s_waitcnt vmcnt(" #n ")" ::: "memory")
; #define PG8_WAIT_L(n) asm volatile("s_waitcnt lgkmcnt(" #n ")" ::: "memory")
; #define PG8_BAR __builtin_amdgcn_s_barrier()
; #define PG8_SCHED __builtin_amdgcn_sched_barrier(0)
; template <class Epi, class Sched>
; __device__ __forceinline__ void gemm_phase(LAS unsigned char* lds, const int lda, const int ldb, const int K, const Sched& S, const Epi& E) {
;     ...
;             PG8_WAIT_V(8); PG8_WAIT_L(0); PG8_BAR;
;             if (last) E.pre(cur, wr, fr, rsv);
;             PG8_MMA(1, 0, At, B0); PG8_MMA(1, 1, At, B1); PG8_BAR; PG8_SCHED;
;         }
.Lrot6:
	s_barrier
.LBB0_1053:
	v_mfma_f32_16x16x32_bf16 v[62:65], v[146:149], v[186:189], v[62:65]
	v_mfma_f32_16x16x32_bf16 v[54:57], v[154:157], v[186:189], v[54:57]
	v_mfma_f32_16x16x32_bf16 v[46:49], v[146:149], v[178:181], v[46:49]
	v_mfma_f32_16x16x32_bf16 v[38:41], v[154:157], v[178:181], v[38:41]
	v_mfma_f32_16x16x32_bf16 v[30:33], v[146:149], v[170:173], v[30:33]
	v_mfma_f32_16x16x32_bf16 v[22:25], v[154:157], v[170:173], v[22:25]
	v_mfma_f32_16x16x32_bf16 v[14:17], v[146:149], v[162:165], v[14:17]
	v_mfma_f32_16x16x32_bf16 v[6:9], v[154:157], v[162:165], v[6:9]
	v_mfma_f32_16x16x32_bf16 v[62:65], v[150:153], v[190:193], v[62:65]
	v_mfma_f32_16x16x32_bf16 v[54:57], v[158:161], v[190:193], v[54:57]
	v_mfma_f32_16x16x32_bf16 v[46:49], v[150:153], v[182:185], v[46:49]
	v_mfma_f32_16x16x32_bf16 v[38:41], v[158:161], v[182:185], v[38:41]
	v_mfma_f32_16x16x32_bf16 v[30:33], v[150:153], v[174:177], v[30:33]
	v_mfma_f32_16x16x32_bf16 v[22:25], v[158:161], v[174:177], v[22:25]
	v_mfma_f32_16x16x32_bf16 v[14:17], v[150:153], v[166:169], v[14:17]
	v_mfma_f32_16x16x32_bf16 v[6:9], v[158:161], v[166:169], v[6:9]
	v_mfma_f32_16x16x32_bf16 v[58:61], v[130:133], v[186:189], v[58:61]
	v_mfma_f32_16x16x32_bf16 v[50:53], v[138:141], v[186:189], v[50:53]
	v_mfma_f32_16x16x32_bf16 v[42:45], v[130:133], v[178:181], v[42:45]
	v_mfma_f32_16x16x32_bf16 v[34:37], v[138:141], v[178:181], v[34:37]
	v_mfma_f32_16x16x32_bf16 v[26:29], v[130:133], v[170:173], v[26:29]
	v_mfma_f32_16x16x32_bf16 v[18:21], v[138:141], v[170:173], v[18:21]
	v_mfma_f32_16x16x32_bf16 v[10:13], v[130:133], v[162:165], v[10:13]
	v_mfma_f32_16x16x32_bf16 v[2:5], v[138:141], v[162:165], v[2:5]
	v_mfma_f32_16x16x32_bf16 v[58:61], v[134:137], v[190:193], v[58:61]
	v_mfma_f32_16x16x32_bf16 v[50:53], v[142:145], v[190:193], v[50:53]
	v_mfma_f32_16x16x32_bf16 v[42:45], v[134:137], v[182:185], v[42:45]
	v_mfma_f32_16x16x32_bf16 v[34:37], v[142:145], v[182:185], v[34:37]
	v_mfma_f32_16x16x32_bf16 v[26:29], v[134:137], v[174:177], v[26:29]
	v_mfma_f32_16x16x32_bf16 v[18:21], v[142:145], v[174:177], v[18:21]
	v_mfma_f32_16x16x32_bf16 v[10:13], v[134:137], v[166:169], v[10:13]
	v_mfma_f32_16x16x32_bf16 v[2:5], v[142:145], v[166:169], v[2:5]
	s_barrier
	s_add_i32 s21, s21, 2
	s_add_u32 s22, s22, 0x100
	s_addc_u32 s23, s23, 0
	s_add_u32 s13, s13, 0x100
	s_addc_u32 s15, s15, 0
	s_cmp_gt_u32 s21, 13
	s_cbranch_scc1 .LBB0_1056

; #define PG8_STAGE(bufoff, gbase, voff) do { _Pragma("unroll") for (int _i = 0; _i < 2; ++_i) \
;         __builtin_amdgcn_global_load_lds((const unsigned*)((const char*)(gbase) + (voff)[_i]), (LAS unsigned*)(lds + (bufoff) + ldsw + _i * 8192), 16, 0, 0); } while (0)
; #define PG8_LDA(dst, b, h) do { _Pragma("unroll") for (int m = 0; m < 4; ++m) _Pragma("unroll") for (int k = 0; k < 2; ++k) dst[m][k] = *(const LAS bf16x8*)(lds + PG8_SA(b, h) + aoff + m * 2048 + k * 1024); } while (0)
; #define PG8_LDB(dst, b, h) do { _Pragma("unroll") for (int n = 0; n < 2; ++n) _Pragma("unroll") for (int k = 0; k < 2; ++k) dst[n][k] = *(const LAS bf16x8*)(lds + PG8_SB(b, h) + boff + n * 2048 + k * 1024); } while (0)
; #define PG8_MMA(ai, bj, At, Bt) do { __builtin_amdgcn_s_setprio(1); _Pragma("unroll") for (int m = 0; m < 4; ++m) _Pragma("unroll") for (int n = 0; n < 2; ++n) _Pragma("unroll") for (int k = 0; k < 2; ++k) \
;         acc[ai][bj][m][n] = __builtin_amdgcn_mfma_f32_16x16x32_bf16(Bt[n][k], At[m][k], acc[ai][bj][m][n], 0, 0, 0); __builtin_amdgcn_s_setprio(0); } while (0)
; #define PG8_WAIT_V(n) asm volatile("s_waitcnt vmcnt(" #n ")" ::: "memory")
; #define PG8_WAIT_L(n) asm volatile("s_waitcnt lgkmcnt(" #n ")" ::: "memory")
; #define PG8_BAR __builtin_amdgcn_s_barrier()
; #define PG8_SCHED __builtin_amdgcn_sched_barrier(0)
; template <class Epi, class Sched>
; __device__ __forceinline__ void gemm_phase(LAS unsigned char* lds, const int lda, const int ldb, const int K, const Sched& S, const Epi& E) {
;     ...
;             PG8_LDB(B0, 1, 0); PG8_LDB(B1, 1, 1); PG8_SCHED; PG8_LDA(At, 1, 0); PG8_STAGE(PG8_SA(0, 1), a2 + hstepA, voffA);
;             PG8_WAIT_V(8); PG8_WAIT_L(0); PG8_BAR; PG8_MMA(0, 0, At, B0); PG8_MMA(0, 1, At, B1); PG8_BAR; PG8_SCHED;
;             PG8_LDA(At, 1, 1); PG8_STAGE(PG8_SB(1, 0), b3, voffB); PG8_STAGE(PG8_SB(1, 1), b3 + hstepB, voffB); PG8_STAGE(PG8_SA(1, 0), a3, voffA);
;             PG8_WAIT_V(8); PG8_WAIT_L(0); PG8_BAR;
;             if (last) E.pre(cur, wr, fr, rsv);
;     __device__ __forceinline__ void pre(const pg8::Unit& u, int wr, int fr, float (&rsv)[8]) const {
;         const float* p = ss + u.pm * 256 + wr * 64 + fr;
; #pragma unroll
;         for (int ai = 0; ai < 2; ++ai)
; #pragma unroll
;             for (int m = 0; m < 4; ++m) rsv[ai * 4 + m] = p[ai * 128 + m * 16];
;     }
.Lpeel6_join:
	v_add_u32_e32 v130, s74, v195
	v_add_u32_e32 v142, s75, v195
	ds_read_b128 v[146:149], v130
	ds_read_b128 v[150:153], v130 offset:1024
	ds_read_b128 v[154:157], v130 offset:2048
	ds_read_b128 v[158:161], v130 offset:3072
	ds_read_b128 v[130:133], v142
	ds_read_b128 v[134:137], v142 offset:1024
	ds_read_b128 v[138:141], v142 offset:2048
	ds_read_b128 v[142:145], v142 offset:3072
	s_mov_b32 m0, s41
	ds_read_b128 v[162:165], v219 offset:32768
	ds_read_b128 v[166:169], v219 offset:33792
	ds_read_b128 v[170:173], v219 offset:34816
	ds_read_b128 v[174:177], v219 offset:35840
	ds_read_b128 v[178:181], v219 offset:36864
	ds_read_b128 v[182:185], v219 offset:37888
	ds_read_b128 v[186:189], v219 offset:38912
	ds_read_b128 v[190:193], v219 offset:39936
	global_load_lds_dwordx4 v202, s[26:27]
	s_mov_b32 m0, s42
	s_nop 0
	global_load_lds_dwordx4 v198, s[26:27]
	s_waitcnt vmcnt(8)
	s_waitcnt lgkmcnt(0)
	s_barrier
	v_mfma_f32_16x16x32_bf16 v[126:129], v[146:149], v[162:165], v[126:129]
	v_mfma_f32_16x16x32_bf16 v[118:121], v[154:157], v[162:165], v[118:121]
	v_mfma_f32_16x16x32_bf16 v[110:113], v[146:149], v[170:173], v[110:113]
	v_mfma_f32_16x16x32_bf16 v[102:105], v[154:157], v[170:173], v[102:105]
	v_mfma_f32_16x16x32_bf16 v[94:97], v[146:149], v[178:181], v[94:97]
	v_mfma_f32_16x16x32_bf16 v[86:89], v[154:157], v[178:181], v[86:89]
	v_mfma_f32_16x16x32_bf16 v[78:81], v[146:149], v[186:189], v[78:81]
	v_mfma_f32_16x16x32_bf16 v[70:73], v[154:157], v[186:189], v[70:73]
	v_mfma_f32_16x16x32_bf16 v[126:129], v[150:153], v[166:169], v[126:129]
	v_mfma_f32_16x16x32_bf16 v[118:121], v[158:161], v[166:169], v[118:121]
	v_mfma_f32_16x16x32_bf16 v[110:113], v[150:153], v[174:177], v[110:113]
	v_mfma_f32_16x16x32_bf16 v[102:105], v[158:161], v[174:177], v[102:105]
	v_mfma_f32_16x16x32_bf16 v[94:97], v[150:153], v[182:185], v[94:97]
	v_mfma_f32_16x16x32_bf16 v[86:89], v[158:161], v[182:185], v[86:89]
	v_mfma_f32_16x16x32_bf16 v[78:81], v[150:153], v[190:193], v[78:81]
	v_mfma_f32_16x16x32_bf16 v[70:73], v[158:161], v[190:193], v[70:73]
	v_mfma_f32_16x16x32_bf16 v[122:125], v[130:133], v[162:165], v[122:125]
	v_mfma_f32_16x16x32_bf16 v[114:117], v[138:141], v[162:165], v[114:117]
	v_mfma_f32_16x16x32_bf16 v[106:109], v[130:133], v[170:173], v[106:109]
	v_mfma_f32_16x16x32_bf16 v[98:101], v[138:141], v[170:173], v[98:101]
	v_mfma_f32_16x16x32_bf16 v[90:93], v[130:133], v[178:181], v[90:93]
	v_mfma_f32_16x16x32_bf16 v[82:85], v[138:141], v[178:181], v[82:85]
	v_mfma_f32_16x16x32_bf16 v[74:77], v[130:133], v[186:189], v[74:77]
	v_mfma_f32_16x16x32_bf16 v[66:69], v[138:141], v[186:189], v[66:69]
	v_mfma_f32_16x16x32_bf16 v[122:125], v[134:137], v[166:169], v[122:125]
	v_mfma_f32_16x16x32_bf16 v[114:117], v[142:145], v[166:169], v[114:117]
	v_mfma_f32_16x16x32_bf16 v[106:109], v[134:137], v[174:177], v[106:109]
	v_mfma_f32_16x16x32_bf16 v[98:101], v[142:145], v[174:177], v[98:101]
	v_mfma_f32_16x16x32_bf16 v[90:93], v[134:137], v[182:185], v[90:93]
	v_mfma_f32_16x16x32_bf16 v[82:85], v[142:145], v[182:185], v[82:85]
	v_mfma_f32_16x16x32_bf16 v[74:77], v[134:137], v[190:193], v[74:77]
	v_mfma_f32_16x16x32_bf16 v[66:69], v[142:145], v[190:193], v[66:69]
	s_barrier
	s_mov_b32 m0, s66
	ds_read_b128 v[186:189], v219 offset:49152
	ds_read_b128 v[190:193], v219 offset:50176
	ds_read_b128 v[178:181], v219 offset:51200
	ds_read_b128 v[182:185], v219 offset:52224
	ds_read_b128 v[170:173], v219 offset:53248
	ds_read_b128 v[174:177], v219 offset:54272
	ds_read_b128 v[162:165], v219 offset:55296
	ds_read_b128 v[166:169], v219 offset:56320
	global_load_lds_dwordx4 v230, s[30:31]
	s_mov_b32 m0, s65
	s_nop 0
	global_load_lds_dwordx4 v231, s[30:31]
	s_mov_b32 m0, s68
	s_nop 0
	global_load_lds_dwordx4 v200, s[24:25]
	s_mov_b32 m0, s67
	s_nop 0
	global_load_lds_dwordx4 v196, s[24:25]
	s_mov_b32 m0, s44
	s_nop 0
	global_load_lds_dwordx4 v232, s[28:29]
	s_mov_b32 m0, s45
	s_nop 0
	global_load_lds_dwordx4 v233, s[28:29]
	s_waitcnt vmcnt(8)
	s_waitcnt lgkmcnt(0)
	s_cbranch_scc1 .Lrot6
	s_barrier
	global_load_dword v228, v[214:215], off
	global_load_dword v227, v[214:215], off offset:64
	global_load_dword v226, v[214:215], off offset:128
	global_load_dword v225, v[214:215], off offset:192
	global_load_dword v224, v[214:215], off offset:512
	global_load_dword v223, v[214:215], off offset:576
	global_load_dword v222, v[214:215], off offset:640
	global_load_dword v221, v[214:215], off offset:704
	s_branch .LBB0_1053
